# also nt: attention query loads (zq, cq) and conv zcb loads, each read once before being overwritten in place
# baseline (speedup 1.0000x reference)
.LBB0_411:
	v_max_i32_e32 v2, 2, v80
	v_add_u32_e32 v0, -2, v2
	v_mov_b32_e32 v1, v195
	v_lshlrev_b64 v[0:1], 11, v[0:1]
	v_lshl_add_u64 v[0:1], v[128:129], 0, v[0:1]
	global_load_dwordx4 v[24:27], v[0:1], off
	v_mov_b32_e32 v1, v195
	v_add_u32_e32 v0, -1, v2
	v_lshlrev_b64 v[0:1], 11, v[0:1]
	v_lshl_add_u64 v[0:1], v[128:129], 0, v[0:1]
	global_load_dwordx4 v[28:31], v[0:1], off
	v_add_u32_e32 v0, 0xffffc000, v80
	s_movk_i32 s0, 0x4000
	v_lshrrev_b32_e32 v194, 5, v0
	v_cmp_gt_i32_e32 vcc, s0, v80
	v_lshlrev_b64 v[0:1], 11, v[194:195]
	v_and_b32_e32 v3, 0x7f0, v80
	v_cndmask_b32_e64 v1, v1, 0, vcc
	v_cndmask_b32_e64 v0, v0, 0, vcc
	v_lshl_add_u64 v[0:1], v[0:1], 2, v[130:131]
	global_load_dwordx4 v[32:35], v[0:1], off
	global_load_dwordx4 v[36:39], v[0:1], off offset:16
	s_movk_i32 s0, 0x1000
	v_cndmask_b32_e32 v104, v158, v3, vcc
	v_lshl_add_u64 v[2:3], v[0:1], 0, s[24:25]
	v_add_co_u32_e64 v0, s[0:1], s0, v0
	v_ashrrev_i32_e32 v81, 31, v80
	s_nop 0
	v_addc_co_u32_e64 v1, s[0:1], 0, v1, s[0:1]
	global_load_dwordx4 v[40:43], v[0:1], off
	global_load_dwordx4 v[44:47], v[2:3], off offset:16
	s_nop 0
	global_load_dwordx4 v[0:3], v[122:123], off offset:16
	global_load_dwordx4 v[12:15], v[122:123], off
	global_load_dwordx4 v[4:7], v[124:125], off offset:16
	global_load_dwordx4 v[16:19], v[124:125], off
	global_load_dwordx4 v[8:11], v[126:127], off offset:16
	global_load_dwordx4 v[20:23], v[126:127], off
	v_lshlrev_b32_e32 v105, 1, v120
	s_waitcnt vmcnt(12)
	v_lshlrev_b64 v[100:101], 11, v[80:81]
	v_or_b32_e32 v48, v100, v105
	v_mov_b32_e32 v49, v101
	v_lshl_add_u64 v[50:51], s[74:75], 0, v[48:49]
	v_lshl_add_u64 v[48:49], s[76:77], 0, v[48:49]
	global_load_dwordx4 v[56:59], v[50:51], off
	global_load_dwordx4 v[106:109], v[48:49], off nt
	v_cmp_eq_u32_e64 s[0:1], 0, v104
	v_lshl_add_u64 v[100:101], v[132:133], 0, v[100:101]
	s_waitcnt vmcnt(13)
	v_and_b32_e32 v48, 0xffff0000, v24
	v_lshlrev_b32_e32 v24, 16, v24
	v_lshlrev_b32_e32 v49, 16, v25
	v_and_b32_e32 v25, 0xffff0000, v25
	v_lshlrev_b32_e32 v50, 16, v26
	s_waitcnt vmcnt(12)
	v_lshlrev_b32_e32 v52, 16, v28
	v_lshlrev_b32_e32 v53, 16, v29
	v_and_b32_e32 v29, 0xffff0000, v29
	v_lshlrev_b32_e32 v55, 16, v31
	v_and_b32_e32 v31, 0xffff0000, v31
	v_and_b32_e32 v26, 0xffff0000, v26
	v_lshlrev_b32_e32 v51, 16, v27
	v_and_b32_e32 v27, 0xffff0000, v27
	v_and_b32_e32 v28, 0xffff0000, v28
	s_waitcnt vmcnt(11)
	v_cndmask_b32_e64 v32, v32, 0, vcc
	v_cndmask_b32_e64 v114, v24, v32, s[0:1]
	v_cndmask_b32_e64 v35, v35, 0, vcc
	s_waitcnt vmcnt(9)
	v_cndmask_b32_e64 v24, v40, 0, vcc
	v_cndmask_b32_e64 v81, v52, v24, s[0:1]
	v_cndmask_b32_e64 v24, v43, 0, vcc
	v_cndmask_b32_e64 v174, v29, v24, s[0:1]
	s_waitcnt vmcnt(8)
	v_cndmask_b32_e64 v24, v47, 0, vcc
	v_cndmask_b32_e64 v175, v31, v24, s[0:1]
	v_add_u32_e32 v24, 1, v80
	v_cndmask_b32_e64 v98, v25, v35, s[0:1]
	v_ashrrev_i32_e32 v25, 31, v24
	v_cndmask_b32_e64 v37, v37, 0, vcc
	v_lshlrev_b64 v[94:95], 11, v[24:25]
	v_cndmask_b32_e64 v39, v39, 0, vcc
	v_cndmask_b32_e64 v154, v26, v37, s[0:1]
	v_cndmask_b32_e64 v26, v41, 0, vcc
	v_or_b32_e32 v24, v94, v105
	v_mov_b32_e32 v25, v95
	v_cndmask_b32_e64 v99, v28, v26, s[0:1]
	v_cndmask_b32_e64 v96, v27, v39, s[0:1]
	v_lshl_add_u64 v[26:27], s[74:75], 0, v[24:25]
	v_lshl_add_u64 v[24:25], s[76:77], 0, v[24:25]
	global_load_dwordx4 v[76:79], v[26:27], off nt
	global_load_dwordx4 v[110:113], v[24:25], off nt
	v_add_u32_e32 v24, 2, v80
	v_ashrrev_i32_e32 v25, 31, v24
	v_lshlrev_b64 v[92:93], 11, v[24:25]
	v_or_b32_e32 v24, v92, v105
	v_mov_b32_e32 v25, v93
	v_lshl_add_u64 v[26:27], s[74:75], 0, v[24:25]
	v_lshl_add_u64 v[24:25], s[76:77], 0, v[24:25]
	global_load_dwordx4 v[72:75], v[26:27], off nt
	global_load_dwordx4 v[68:71], v[24:25], off nt
	v_add_u32_e32 v24, 3, v80
	v_ashrrev_i32_e32 v25, 31, v24
	v_lshlrev_b64 v[90:91], 11, v[24:25]
	v_or_b32_e32 v24, v90, v105
	v_mov_b32_e32 v25, v91
	v_lshl_add_u64 v[26:27], s[74:75], 0, v[24:25]
	v_lshl_add_u64 v[24:25], s[76:77], 0, v[24:25]
	global_load_dwordx4 v[64:67], v[26:27], off nt
	global_load_dwordx4 v[60:63], v[24:25], off nt
	s_waitcnt vmcnt(6)
	v_lshlrev_b32_e32 v117, 16, v106
	v_and_b32_e32 v155, 0xffff0000, v106
	v_lshlrev_b32_e32 v176, 16, v107
	v_and_b32_e32 v177, 0xffff0000, v107
	v_mov_b32_e32 v106, v12
	v_mov_b32_e32 v107, v20
	v_add_u32_e32 v24, 4, v80
	v_ashrrev_i32_e32 v25, 31, v24
	v_cndmask_b32_e64 v36, v36, 0, vcc
	v_lshlrev_b64 v[88:89], 11, v[24:25]
	v_lshlrev_b32_e32 v54, 16, v30
	v_cndmask_b32_e64 v34, v34, 0, vcc
	v_cndmask_b32_e64 v116, v50, v36, s[0:1]
	v_cndmask_b32_e64 v32, v44, 0, vcc
	v_or_b32_e32 v24, v88, v105
	v_mov_b32_e32 v25, v89
	v_lshlrev_b32_e32 v119, 16, v108
	v_and_b32_e32 v157, 0xffff0000, v108
	v_lshlrev_b32_e32 v178, 16, v109
	v_and_b32_e32 v179, 0xffff0000, v109
	v_mov_b32_e32 v108, v0
	v_mov_b32_e32 v109, v8
	v_cndmask_b32_e64 v33, v33, 0, vcc
	v_cndmask_b32_e64 v38, v38, 0, vcc
	v_cndmask_b32_e64 v156, v49, v34, s[0:1]
	v_cndmask_b32_e64 v34, v42, 0, vcc
	v_cndmask_b32_e64 v36, v46, 0, vcc
	v_cndmask_b32_e64 v97, v54, v32, s[0:1]
	v_lshl_add_u64 v[26:27], s[74:75], 0, v[24:25]
	v_cndmask_b32_e64 v118, v48, v33, s[0:1]
	v_cndmask_b32_e64 v102, v51, v38, s[0:1]
	v_cndmask_b32_e64 v172, v53, v34, s[0:1]
	v_cndmask_b32_e64 v173, v55, v36, s[0:1]
	v_lshl_add_u64 v[24:25], s[76:77], 0, v[24:25]
	global_load_dwordx4 v[52:55], v[26:27], off nt
	global_load_dwordx4 v[48:51], v[24:25], off nt
	v_mov_b32_e32 v160, v13
	v_mov_b32_e32 v161, v21
	v_add_u32_e32 v24, 5, v80
	v_ashrrev_i32_e32 v25, 31, v24
	v_lshlrev_b64 v[86:87], 11, v[24:25]
	v_and_b32_e32 v30, 0xffff0000, v30
	v_cndmask_b32_e64 v33, v45, 0, vcc
	v_or_b32_e32 v24, v86, v105
	v_mov_b32_e32 v25, v87
	v_mov_b32_e32 v162, v1
	v_mov_b32_e32 v163, v9
	v_cndmask_b32_e64 v103, v30, v33, s[0:1]
	v_lshl_add_u64 v[26:27], s[74:75], 0, v[24:25]
	v_lshl_add_u64 v[24:25], s[76:77], 0, v[24:25]
	global_load_dwordx4 v[44:47], v[26:27], off nt
	global_load_dwordx4 v[40:43], v[24:25], off nt
	v_mov_b32_e32 v164, v14
	v_mov_b32_e32 v165, v22
	v_add_u32_e32 v24, 6, v80
	v_ashrrev_i32_e32 v25, 31, v24
	v_lshlrev_b64 v[84:85], 11, v[24:25]
	v_or_b32_e32 v24, v84, v105
	v_mov_b32_e32 v25, v85
	v_mov_b32_e32 v166, v2
	v_mov_b32_e32 v167, v10
	v_lshl_add_u64 v[26:27], s[74:75], 0, v[24:25]
	v_lshl_add_u64 v[24:25], s[76:77], 0, v[24:25]
	global_load_dwordx4 v[36:39], v[26:27], off nt
	global_load_dwordx4 v[32:35], v[24:25], off nt
	v_add_u32_e32 v24, 7, v80
	s_waitcnt vmcnt(10)
	v_lshlrev_b32_e32 v180, 16, v110
	v_and_b32_e32 v181, 0xffff0000, v110
	v_lshlrev_b32_e32 v110, 16, v56
	v_mov_b32_e32 v115, v110
	v_pk_mul_f32 v[106:107], v[106:107], v[114:115]
	v_lshlrev_b32_e32 v182, 16, v111
	v_fma_f32 v106, v16, v81, v106
	v_add_f32_e32 v106, v106, v107
	v_and_b32_e32 v183, 0xffff0000, v111
	v_lshlrev_b32_e32 v111, 16, v76
	v_mul_f32_e32 v114, v106, v117
	v_mov_b32_e32 v106, v16
	v_mov_b32_e32 v107, v20
	v_pk_mul_f32 v[106:107], v[106:107], v[110:111]
	v_lshlrev_b32_e32 v184, 16, v112
	v_fma_f32 v81, v12, v81, v106
	v_lshlrev_b32_e32 v106, 16, v58
	v_mov_b32_e32 v117, v106
	v_pk_mul_f32 v[108:109], v[108:109], v[116:117]
	v_add_f32_e32 v81, v81, v107
	v_fma_f32 v108, v4, v97, v108
	v_add_f32_e32 v108, v108, v109
	v_lshlrev_b32_e32 v107, 16, v78
	v_mul_f32_e32 v116, v108, v119
	v_mov_b32_e32 v108, v4
	v_mov_b32_e32 v109, v8
	v_pk_mul_f32 v[108:109], v[108:109], v[106:107]
	v_and_b32_e32 v185, 0xffff0000, v112
	v_fma_f32 v97, v0, v97, v108
	v_and_b32_e32 v108, 0xffff0000, v56
	v_mov_b32_e32 v119, v108
	v_lshlrev_b32_e32 v186, 16, v113
	v_and_b32_e32 v187, 0xffff0000, v113
	v_pk_mul_f32 v[112:113], v[160:161], v[118:119]
	v_add_f32_e32 v97, v97, v109
	v_fma_f32 v56, v17, v99, v112
	v_and_b32_e32 v109, 0xffff0000, v76
	v_add_f32_e32 v56, v56, v113
	v_mov_b32_e32 v112, v17
	v_mov_b32_e32 v113, v21
	v_pk_mul_f32 v[112:113], v[112:113], v[108:109]
	v_mul_f32_e32 v56, v56, v155
	v_fma_f32 v76, v13, v99, v112
	v_and_b32_e32 v112, 0xffff0000, v58
	v_mov_b32_e32 v155, v112
	v_cvt_pk_bf16_f32 v56, v114, v56
	v_pk_mul_f32 v[114:115], v[162:163], v[154:155]
	v_add_f32_e32 v76, v76, v113
	v_fma_f32 v58, v5, v103, v114
	v_and_b32_e32 v113, 0xffff0000, v78
	v_add_f32_e32 v58, v58, v115
	v_mov_b32_e32 v114, v5
	v_mov_b32_e32 v115, v9
	v_pk_mul_f32 v[114:115], v[114:115], v[112:113]
	v_mul_f32_e32 v118, v76, v181
	v_fma_f32 v76, v1, v103, v114
	v_lshlrev_b32_e32 v114, 16, v57
	v_mul_f32_e32 v58, v58, v157
	v_mov_b32_e32 v157, v114
	v_cvt_pk_bf16_f32 v58, v116, v58
	v_add_f32_e32 v76, v76, v115
	v_pk_mul_f32 v[116:117], v[164:165], v[156:157]
	v_mul_f32_e32 v119, v76, v185
	v_fma_f32 v76, v18, v172, v116
	v_lshlrev_b32_e32 v115, 16, v77
	v_add_f32_e32 v76, v76, v117
	v_mov_b32_e32 v116, v18
	v_mov_b32_e32 v117, v22
	v_pk_mul_f32 v[116:117], v[116:117], v[114:115]
	v_mul_f32_e32 v78, v76, v176
	v_fma_f32 v76, v14, v172, v116
	v_lshlrev_b32_e32 v116, 16, v59
	v_mov_b32_e32 v103, v116
	v_add_f32_e32 v76, v76, v117
	v_pk_mul_f32 v[102:103], v[166:167], v[102:103]
	v_mul_f32_e32 v154, v76, v182
	v_fma_f32 v76, v6, v173, v102
	v_lshlrev_b32_e32 v117, 16, v79
	v_add_f32_e32 v76, v76, v103
	v_mov_b32_e32 v102, v6
	v_mov_b32_e32 v103, v10
	v_pk_mul_f32 v[102:103], v[102:103], v[116:117]
	v_mul_f32_e32 v155, v76, v178
	v_fma_f32 v76, v2, v173, v102
	v_ashrrev_i32_e32 v25, 31, v24
	v_add_f32_e32 v76, v76, v103
	v_lshlrev_b64 v[82:83], 11, v[24:25]
	v_mul_f32_e32 v102, v76, v186
	v_and_b32_e32 v76, 0xffff0000, v57
	v_or_b32_e32 v24, v82, v105
	v_mov_b32_e32 v25, v83
	v_mov_b32_e32 v168, v15
	v_mov_b32_e32 v169, v23
	v_mov_b32_e32 v99, v76
	v_lshl_add_u64 v[26:27], s[74:75], 0, v[24:25]
	v_lshl_add_u64 v[24:25], s[76:77], 0, v[24:25]
	v_pk_mul_f32 v[98:99], v[168:169], v[98:99]
	global_load_dwordx4 v[28:31], v[26:27], off nt
	s_nop 0
	global_load_dwordx4 v[24:27], v[24:25], off nt
	v_fma_f32 v57, v19, v174, v98
	v_and_b32_e32 v77, 0xffff0000, v77
	v_add_f32_e32 v57, v57, v99
	v_mov_b32_e32 v98, v19
	v_mov_b32_e32 v99, v23
	v_mul_f32_e32 v57, v57, v177
	v_pk_mul_f32 v[98:99], v[98:99], v[76:77]
	v_cvt_pk_bf16_f32 v57, v78, v57
	v_fma_f32 v78, v15, v174, v98
	v_add_f32_e32 v78, v78, v99
	v_mul_f32_e32 v98, v78, v183
	v_and_b32_e32 v78, 0xffff0000, v59
	v_mov_b32_e32 v170, v3
	v_mov_b32_e32 v171, v11
	v_mul_f32_e32 v81, v81, v180
	v_mul_f32_e32 v180, v97, v184
	v_mov_b32_e32 v97, v78
	v_pk_mul_f32 v[96:97], v[170:171], v[96:97]
	v_and_b32_e32 v79, 0xffff0000, v79
	v_fma_f32 v59, v7, v175, v96
	v_add_f32_e32 v59, v59, v97
	v_mul_f32_e32 v59, v59, v179
	v_cvt_pk_bf16_f32 v59, v155, v59
	global_store_dwordx4 v[100:101], v[56:59], off
	v_lshl_add_u64 v[94:95], v[132:133], 0, v[94:95]
	v_mov_b32_e32 v99, v112
	v_mov_b32_e32 v56, v7
	v_mov_b32_e32 v57, v11
	v_pk_mul_f32 v[56:57], v[56:57], v[78:79]
	v_cvt_pk_bf16_f32 v58, v180, v119
	v_fma_f32 v56, v3, v175, v56
	v_add_f32_e32 v56, v56, v57
	v_mul_f32_e32 v59, v56, v187
	v_cvt_pk_bf16_f32 v56, v81, v118
	v_cvt_pk_bf16_f32 v57, v154, v98
	v_cvt_pk_bf16_f32 v59, v102, v59
	global_store_dwordx4 v[94:95], v[56:59], off
	v_mov_b32_e32 v112, v107
	s_waitcnt vmcnt(13)
	v_lshlrev_b32_e32 v94, 16, v72
	v_mov_b32_e32 v59, v108
	v_mov_b32_e32 v108, v111
	v_mov_b32_e32 v58, v110
	v_pk_mul_f32 v[96:97], v[16:17], v[108:109]
	v_and_b32_e32 v95, 0xffff0000, v72
	v_pk_fma_f32 v[58:59], v[12:13], v[58:59], v[96:97]
	v_mov_b32_e32 v98, v106
	v_pk_mul_f32 v[100:101], v[4:5], v[112:113]
	s_waitcnt vmcnt(12)
	v_lshlrev_b32_e32 v56, 16, v68
	v_and_b32_e32 v57, 0xffff0000, v68
	v_pk_fma_f32 v[58:59], v[20:21], v[94:95], v[58:59]
	v_lshlrev_b32_e32 v96, 16, v74
	v_and_b32_e32 v97, 0xffff0000, v74
	v_pk_fma_f32 v[98:99], v[0:1], v[98:99], v[100:101]
	v_pk_mul_f32 v[56:57], v[58:59], v[56:57]
	v_lshlrev_b32_e32 v58, 16, v70
	v_and_b32_e32 v59, 0xffff0000, v70
	v_pk_fma_f32 v[98:99], v[8:9], v[96:97], v[98:99]
	v_lshlrev_b32_e32 v72, 16, v73
	v_pk_mul_f32 v[58:59], v[98:99], v[58:59]
	v_mov_b32_e32 v99, v76
	v_mov_b32_e32 v76, v115
	v_mov_b32_e32 v98, v114
	v_pk_mul_f32 v[100:101], v[18:19], v[76:77]
	v_and_b32_e32 v73, 0xffff0000, v73
	v_pk_fma_f32 v[98:99], v[14:15], v[98:99], v[100:101]
	v_lshlrev_b32_e32 v68, 16, v69
	v_and_b32_e32 v69, 0xffff0000, v69
	v_pk_fma_f32 v[98:99], v[22:23], v[72:73], v[98:99]
	v_lshlrev_b32_e32 v74, 16, v75
	v_pk_mul_f32 v[68:69], v[98:99], v[68:69]
	v_mov_b32_e32 v99, v78
	v_mov_b32_e32 v78, v117
	v_mov_b32_e32 v98, v116
	v_pk_mul_f32 v[100:101], v[6:7], v[78:79]
	v_and_b32_e32 v75, 0xffff0000, v75
	v_pk_fma_f32 v[98:99], v[2:3], v[98:99], v[100:101]
	v_lshlrev_b32_e32 v70, 16, v71
	v_and_b32_e32 v71, 0xffff0000, v71
	v_pk_fma_f32 v[98:99], v[10:11], v[74:75], v[98:99]
	v_cvt_pk_bf16_f32 v56, v56, v57
	v_pk_mul_f32 v[70:71], v[98:99], v[70:71]
	v_cvt_pk_bf16_f32 v57, v68, v69
	v_cvt_pk_bf16_f32 v58, v58, v59
	v_cvt_pk_bf16_f32 v59, v70, v71
	v_lshl_add_u64 v[68:69], v[132:133], 0, v[92:93]
	global_store_dwordx4 v[68:69], v[56:59], off
	s_waitcnt vmcnt(12)
	v_lshlrev_b32_e32 v68, 16, v64
	v_and_b32_e32 v69, 0xffff0000, v64
	v_pk_mul_f32 v[58:59], v[16:17], v[94:95]
	v_pk_mul_f32 v[92:93], v[4:5], v[96:97]
	v_pk_fma_f32 v[58:59], v[12:13], v[108:109], v[58:59]
	s_waitcnt vmcnt(11)
	v_lshlrev_b32_e32 v56, 16, v60
	v_and_b32_e32 v57, 0xffff0000, v60
	v_pk_fma_f32 v[58:59], v[20:21], v[68:69], v[58:59]
	v_lshlrev_b32_e32 v70, 16, v66
	v_and_b32_e32 v71, 0xffff0000, v66
	v_pk_fma_f32 v[92:93], v[0:1], v[112:113], v[92:93]
	v_pk_mul_f32 v[56:57], v[58:59], v[56:57]
	v_lshlrev_b32_e32 v58, 16, v62
	v_and_b32_e32 v59, 0xffff0000, v62
	v_pk_fma_f32 v[92:93], v[8:9], v[70:71], v[92:93]
	v_lshlrev_b32_e32 v64, 16, v65
	v_pk_mul_f32 v[58:59], v[92:93], v[58:59]
	v_pk_mul_f32 v[92:93], v[18:19], v[72:73]
	v_and_b32_e32 v65, 0xffff0000, v65
	v_pk_fma_f32 v[76:77], v[14:15], v[76:77], v[92:93]
	v_lshlrev_b32_e32 v60, 16, v61
	v_and_b32_e32 v61, 0xffff0000, v61
	v_pk_fma_f32 v[76:77], v[22:23], v[64:65], v[76:77]
	v_lshlrev_b32_e32 v66, 16, v67
	v_pk_mul_f32 v[60:61], v[76:77], v[60:61]
	v_pk_mul_f32 v[76:77], v[6:7], v[74:75]
	v_and_b32_e32 v67, 0xffff0000, v67
	v_pk_fma_f32 v[76:77], v[2:3], v[78:79], v[76:77]
	v_lshlrev_b32_e32 v62, 16, v63
	v_and_b32_e32 v63, 0xffff0000, v63
	v_pk_fma_f32 v[76:77], v[10:11], v[66:67], v[76:77]
	v_cvt_pk_bf16_f32 v56, v56, v57
	v_pk_mul_f32 v[62:63], v[76:77], v[62:63]
	v_cvt_pk_bf16_f32 v57, v60, v61
	v_cvt_pk_bf16_f32 v58, v58, v59
	v_cvt_pk_bf16_f32 v59, v62, v63
	v_lshl_add_u64 v[60:61], v[132:133], 0, v[90:91]
	global_store_dwordx4 v[60:61], v[56:59], off
	v_pk_mul_f32 v[60:61], v[16:17], v[68:69]
	v_pk_mul_f32 v[76:77], v[4:5], v[70:71]
	s_waitcnt vmcnt(11)
	v_lshlrev_b32_e32 v56, 16, v52
	v_and_b32_e32 v57, 0xffff0000, v52
	v_pk_fma_f32 v[60:61], v[12:13], v[94:95], v[60:61]
	s_waitcnt vmcnt(10)
	v_lshlrev_b32_e32 v58, 16, v48
	v_and_b32_e32 v59, 0xffff0000, v48
	v_pk_fma_f32 v[60:61], v[20:21], v[56:57], v[60:61]
	v_pk_fma_f32 v[76:77], v[0:1], v[96:97], v[76:77]
	v_pk_mul_f32 v[58:59], v[60:61], v[58:59]
	v_lshlrev_b32_e32 v60, 16, v54
	v_and_b32_e32 v61, 0xffff0000, v54
	v_lshlrev_b32_e32 v62, 16, v50
	v_and_b32_e32 v63, 0xffff0000, v50
	v_pk_fma_f32 v[76:77], v[8:9], v[60:61], v[76:77]
	v_lshlrev_b32_e32 v52, 16, v53
	v_pk_mul_f32 v[62:63], v[76:77], v[62:63]
	v_pk_mul_f32 v[76:77], v[18:19], v[64:65]
	v_and_b32_e32 v53, 0xffff0000, v53
	v_pk_fma_f32 v[72:73], v[14:15], v[72:73], v[76:77]
	v_lshlrev_b32_e32 v48, 16, v49
	v_and_b32_e32 v49, 0xffff0000, v49
	v_pk_fma_f32 v[72:73], v[22:23], v[52:53], v[72:73]
	v_lshlrev_b32_e32 v54, 16, v55
	v_pk_mul_f32 v[72:73], v[72:73], v[48:49]
	v_lshlrev_b32_e32 v48, 16, v51
	v_and_b32_e32 v49, 0xffff0000, v51
	v_pk_mul_f32 v[50:51], v[6:7], v[66:67]
	v_and_b32_e32 v55, 0xffff0000, v55
	v_pk_fma_f32 v[50:51], v[2:3], v[74:75], v[50:51]
	s_waitcnt vmcnt(7)
	v_lshlrev_b32_e32 v78, 16, v36
	v_pk_fma_f32 v[50:51], v[10:11], v[54:55], v[50:51]
	v_and_b32_e32 v79, 0xffff0000, v36
	v_pk_mul_f32 v[74:75], v[50:51], v[48:49]
	v_cvt_pk_bf16_f32 v48, v58, v59
	v_cvt_pk_bf16_f32 v49, v72, v73
	v_cvt_pk_bf16_f32 v50, v62, v63
	v_cvt_pk_bf16_f32 v51, v74, v75
	v_lshl_add_u64 v[58:59], v[132:133], 0, v[88:89]
	global_store_dwordx4 v[58:59], v[48:51], off
	v_pk_mul_f32 v[58:59], v[16:17], v[56:57]
	v_lshlrev_b32_e32 v62, 16, v42
	v_lshlrev_b32_e32 v48, 16, v44
	v_and_b32_e32 v49, 0xffff0000, v44
	v_pk_fma_f32 v[58:59], v[12:13], v[68:69], v[58:59]
	v_lshlrev_b32_e32 v50, 16, v40
	v_and_b32_e32 v51, 0xffff0000, v40
	v_pk_fma_f32 v[58:59], v[20:21], v[48:49], v[58:59]
	v_pk_mul_f32 v[68:69], v[4:5], v[60:61]
	v_pk_mul_f32 v[50:51], v[58:59], v[50:51]
	v_lshlrev_b32_e32 v58, 16, v46
	v_and_b32_e32 v59, 0xffff0000, v46
	v_pk_fma_f32 v[68:69], v[0:1], v[70:71], v[68:69]
	v_and_b32_e32 v63, 0xffff0000, v42
	v_pk_fma_f32 v[68:69], v[8:9], v[58:59], v[68:69]
	v_lshlrev_b32_e32 v44, 16, v45
	v_pk_mul_f32 v[62:63], v[68:69], v[62:63]
	v_pk_mul_f32 v[68:69], v[18:19], v[52:53]
	v_and_b32_e32 v45, 0xffff0000, v45
	v_pk_fma_f32 v[64:65], v[14:15], v[64:65], v[68:69]
	v_lshlrev_b32_e32 v40, 16, v41
	v_and_b32_e32 v41, 0xffff0000, v41
	v_pk_fma_f32 v[64:65], v[22:23], v[44:45], v[64:65]
	v_lshlrev_b32_e32 v46, 16, v47
	v_pk_mul_f32 v[64:65], v[64:65], v[40:41]
	v_lshlrev_b32_e32 v40, 16, v43
	v_and_b32_e32 v41, 0xffff0000, v43
	v_pk_mul_f32 v[42:43], v[6:7], v[54:55]
	v_and_b32_e32 v47, 0xffff0000, v47
	v_pk_fma_f32 v[42:43], v[2:3], v[66:67], v[42:43]
	v_lshlrev_b32_e32 v106, 16, v37
	v_pk_fma_f32 v[42:43], v[10:11], v[46:47], v[42:43]
	v_and_b32_e32 v107, 0xffff0000, v37
	v_pk_mul_f32 v[66:67], v[42:43], v[40:41]
	v_cvt_pk_bf16_f32 v40, v50, v51
	v_cvt_pk_bf16_f32 v41, v64, v65
	v_cvt_pk_bf16_f32 v42, v62, v63
	v_cvt_pk_bf16_f32 v43, v66, v67
	v_lshl_add_u64 v[50:51], v[132:133], 0, v[86:87]
	global_store_dwordx4 v[50:51], v[40:43], off
	v_pk_mul_f32 v[36:37], v[18:19], v[44:45]
	v_pk_mul_f32 v[50:51], v[4:5], v[58:59]
	v_pk_mul_f32 v[42:43], v[16:17], v[48:49]
	v_pk_fma_f32 v[36:37], v[14:15], v[52:53], v[36:37]
	v_pk_fma_f32 v[42:43], v[12:13], v[56:57], v[42:43]
	s_waitcnt vmcnt(8)
	v_lshlrev_b32_e32 v40, 16, v32
	v_and_b32_e32 v41, 0xffff0000, v32
	v_pk_fma_f32 v[42:43], v[20:21], v[78:79], v[42:43]
	v_lshlrev_b32_e32 v32, 16, v33
	v_and_b32_e32 v33, 0xffff0000, v33
	v_pk_fma_f32 v[36:37], v[22:23], v[106:107], v[36:37]
	v_pk_mul_f32 v[40:41], v[42:43], v[40:41]
	v_lshlrev_b32_e32 v42, 16, v34
	v_and_b32_e32 v43, 0xffff0000, v34
	v_pk_mul_f32 v[36:37], v[36:37], v[32:33]
	v_lshlrev_b32_e32 v32, 16, v35
	v_and_b32_e32 v33, 0xffff0000, v35
	v_pk_mul_f32 v[34:35], v[6:7], v[46:47]
	v_lshlrev_b32_e32 v102, 16, v38
	v_and_b32_e32 v103, 0xffff0000, v38
	v_pk_fma_f32 v[50:51], v[0:1], v[60:61], v[50:51]
	v_lshlrev_b32_e32 v108, 16, v39
	v_and_b32_e32 v109, 0xffff0000, v39
	v_pk_fma_f32 v[34:35], v[2:3], v[54:55], v[34:35]
	v_pk_fma_f32 v[50:51], v[8:9], v[102:103], v[50:51]
	v_pk_fma_f32 v[34:35], v[10:11], v[108:109], v[34:35]
	v_pk_mul_f32 v[42:43], v[50:51], v[42:43]
	v_pk_mul_f32 v[38:39], v[34:35], v[32:33]
	v_cvt_pk_bf16_f32 v32, v40, v41
	v_cvt_pk_bf16_f32 v33, v36, v37
	v_cvt_pk_bf16_f32 v34, v42, v43
	v_cvt_pk_bf16_f32 v35, v38, v39
	v_lshl_add_u64 v[36:37], v[132:133], 0, v[84:85]
	global_store_dwordx4 v[36:37], v[32:35], off
	s_waitcnt vmcnt(8)
	v_lshlrev_b32_e32 v110, 16, v28
	v_and_b32_e32 v111, 0xffff0000, v28
	v_pk_mul_f32 v[34:35], v[16:17], v[78:79]
	v_lshlrev_b32_e32 v114, 16, v29
	v_and_b32_e32 v115, 0xffff0000, v29
	v_pk_mul_f32 v[28:29], v[18:19], v[106:107]
	v_pk_fma_f32 v[34:35], v[12:13], v[48:49], v[34:35]
	v_pk_fma_f32 v[28:29], v[14:15], v[44:45], v[28:29]
	s_waitcnt vmcnt(7)
	v_lshlrev_b32_e32 v32, 16, v24
	v_and_b32_e32 v33, 0xffff0000, v24
	v_pk_fma_f32 v[34:35], v[20:21], v[110:111], v[34:35]
	v_lshlrev_b32_e32 v24, 16, v25
	v_and_b32_e32 v25, 0xffff0000, v25
	v_pk_fma_f32 v[28:29], v[22:23], v[114:115], v[28:29]
	v_pk_mul_f32 v[32:33], v[34:35], v[32:33]
	v_lshlrev_b32_e32 v34, 16, v26
	v_and_b32_e32 v35, 0xffff0000, v26
	v_pk_mul_f32 v[36:37], v[4:5], v[102:103]
	v_pk_mul_f32 v[28:29], v[28:29], v[24:25]
	v_lshlrev_b32_e32 v24, 16, v27
	v_and_b32_e32 v25, 0xffff0000, v27
	v_pk_mul_f32 v[26:27], v[6:7], v[108:109]
	v_lshlrev_b32_e32 v112, 16, v30
	v_and_b32_e32 v113, 0xffff0000, v30
	v_pk_fma_f32 v[36:37], v[0:1], v[58:59], v[36:37]
	v_lshlrev_b32_e32 v116, 16, v31
	v_and_b32_e32 v117, 0xffff0000, v31
	v_pk_fma_f32 v[26:27], v[2:3], v[46:47], v[26:27]
	v_pk_fma_f32 v[36:37], v[8:9], v[112:113], v[36:37]
	v_pk_fma_f32 v[26:27], v[10:11], v[116:117], v[26:27]
	v_pk_mul_f32 v[34:35], v[36:37], v[34:35]
	v_pk_mul_f32 v[30:31], v[26:27], v[24:25]
	v_cvt_pk_bf16_f32 v24, v32, v33
	v_cvt_pk_bf16_f32 v25, v28, v29
	v_cvt_pk_bf16_f32 v26, v34, v35
	v_cvt_pk_bf16_f32 v27, v30, v31
	v_lshl_add_u64 v[28:29], v[132:133], 0, v[82:83]
	global_store_dwordx4 v[28:29], v[24:27], off
	v_pk_mul_f32 v[164:165], v[16:17], v[110:111]
	v_pk_mul_f32 v[166:167], v[4:5], v[112:113]
	v_add_u32_e32 v24, 8, v80
	v_ashrrev_i32_e32 v25, 31, v24
	v_lshlrev_b64 v[118:119], 11, v[24:25]
	v_or_b32_e32 v24, v118, v105
	v_mov_b32_e32 v25, v119
	v_lshl_add_u64 v[26:27], s[74:75], 0, v[24:25]
	global_load_dwordx4 v[74:77], v[26:27], off nt
	v_lshl_add_u64 v[24:25], s[76:77], 0, v[24:25]
	global_load_dwordx4 v[82:85], v[24:25], off nt
	v_add_u32_e32 v24, 9, v80
	v_ashrrev_i32_e32 v25, 31, v24
	v_lshlrev_b64 v[154:155], 11, v[24:25]
	v_or_b32_e32 v24, v154, v105
	v_mov_b32_e32 v25, v155
	v_lshl_add_u64 v[26:27], s[74:75], 0, v[24:25]
	v_lshl_add_u64 v[24:25], s[76:77], 0, v[24:25]
	global_load_dwordx4 v[86:89], v[26:27], off nt
	global_load_dwordx4 v[90:93], v[24:25], off nt
	v_add_u32_e32 v24, 10, v80
	v_ashrrev_i32_e32 v25, 31, v24
	v_lshlrev_b64 v[156:157], 11, v[24:25]
	v_or_b32_e32 v24, v156, v105
	v_mov_b32_e32 v25, v157
	v_lshl_add_u64 v[26:27], s[74:75], 0, v[24:25]
	v_lshl_add_u64 v[24:25], s[76:77], 0, v[24:25]
	global_load_dwordx4 v[94:97], v[26:27], off nt
	global_load_dwordx4 v[98:101], v[24:25], off nt
	v_add_u32_e32 v24, 11, v80
	v_ashrrev_i32_e32 v25, 31, v24
	v_lshlrev_b64 v[72:73], 11, v[24:25]
	v_or_b32_e32 v24, v72, v105
	v_mov_b32_e32 v25, v73
	v_lshl_add_u64 v[26:27], s[74:75], 0, v[24:25]
	v_lshl_add_u64 v[24:25], s[76:77], 0, v[24:25]
	global_load_dwordx4 v[60:63], v[26:27], off nt
	global_load_dwordx4 v[56:59], v[24:25], off nt
	v_add_u32_e32 v24, 12, v80
	v_ashrrev_i32_e32 v25, 31, v24
	v_lshlrev_b64 v[70:71], 11, v[24:25]
	v_or_b32_e32 v24, v70, v105
	v_mov_b32_e32 v25, v71
	v_lshl_add_u64 v[26:27], s[74:75], 0, v[24:25]
	v_lshl_add_u64 v[24:25], s[76:77], 0, v[24:25]
	global_load_dwordx4 v[52:55], v[26:27], off nt
	global_load_dwordx4 v[48:51], v[24:25], off nt
	v_add_u32_e32 v24, 13, v80
	v_ashrrev_i32_e32 v25, 31, v24
	v_lshlrev_b64 v[68:69], 11, v[24:25]
	v_or_b32_e32 v24, v68, v105
	v_mov_b32_e32 v25, v69
	v_lshl_add_u64 v[26:27], s[74:75], 0, v[24:25]
	v_lshl_add_u64 v[24:25], s[76:77], 0, v[24:25]
	global_load_dwordx4 v[44:47], v[26:27], off nt
	global_load_dwordx4 v[40:43], v[24:25], off nt
	v_add_u32_e32 v24, 14, v80
	v_ashrrev_i32_e32 v25, 31, v24
	v_lshlrev_b64 v[66:67], 11, v[24:25]
	v_or_b32_e32 v24, v66, v105
	v_mov_b32_e32 v25, v67
	v_lshl_add_u64 v[26:27], s[74:75], 0, v[24:25]
	v_lshl_add_u64 v[24:25], s[76:77], 0, v[24:25]
	global_load_dwordx4 v[36:39], v[26:27], off nt
	global_load_dwordx4 v[32:35], v[24:25], off nt
	v_pk_fma_f32 v[78:79], v[12:13], v[78:79], v[164:165]
	v_add_u32_e32 v24, 15, v80
	v_pk_fma_f32 v[102:103], v[0:1], v[102:103], v[166:167]
	v_ashrrev_i32_e32 v25, 31, v24
	v_lshlrev_b64 v[64:65], 11, v[24:25]
	v_or_b32_e32 v24, v64, v105
	v_mov_b32_e32 v25, v65
	v_lshl_add_u64 v[26:27], s[74:75], 0, v[24:25]
	v_lshl_add_u64 v[24:25], s[76:77], 0, v[24:25]
	global_load_dwordx4 v[28:31], v[26:27], off nt
	s_nop 0
	global_load_dwordx4 v[24:27], v[24:25], off nt
	v_lshl_add_u64 v[72:73], v[132:133], 0, v[72:73]
	s_waitcnt vmcnt(15)
	v_lshlrev_b32_e32 v160, 16, v74
	v_and_b32_e32 v161, 0xffff0000, v74
	s_waitcnt vmcnt(14)
	v_lshlrev_b32_e32 v162, 16, v82
	v_and_b32_e32 v163, 0xffff0000, v82
	v_pk_fma_f32 v[78:79], v[20:21], v[160:161], v[78:79]
	v_lshlrev_b32_e32 v164, 16, v84
	v_pk_mul_f32 v[78:79], v[78:79], v[162:163]
	v_lshlrev_b32_e32 v162, 16, v76
	v_and_b32_e32 v163, 0xffff0000, v76
	v_and_b32_e32 v165, 0xffff0000, v84
	v_pk_fma_f32 v[102:103], v[8:9], v[162:163], v[102:103]
	v_lshlrev_b32_e32 v74, 16, v83
	v_pk_mul_f32 v[102:103], v[102:103], v[164:165]
	v_lshlrev_b32_e32 v164, 16, v75
	v_and_b32_e32 v165, 0xffff0000, v75
	v_and_b32_e32 v75, 0xffff0000, v83
	v_pk_mul_f32 v[82:83], v[18:19], v[114:115]
	s_nop 0
	v_pk_fma_f32 v[82:83], v[14:15], v[106:107], v[82:83]
	v_lshlrev_b32_e32 v106, 16, v77
	v_and_b32_e32 v107, 0xffff0000, v77
	v_pk_mul_f32 v[76:77], v[6:7], v[116:117]
	v_pk_fma_f32 v[82:83], v[22:23], v[164:165], v[82:83]
	v_pk_fma_f32 v[76:77], v[2:3], v[108:109], v[76:77]
	v_pk_mul_f32 v[82:83], v[82:83], v[74:75]
	v_lshlrev_b32_e32 v74, 16, v85
	v_and_b32_e32 v75, 0xffff0000, v85
	v_pk_fma_f32 v[76:77], v[10:11], v[106:107], v[76:77]
	s_nop 0
	v_pk_mul_f32 v[84:85], v[76:77], v[74:75]
	v_cvt_pk_bf16_f32 v74, v78, v79
	v_cvt_pk_bf16_f32 v75, v82, v83
	v_cvt_pk_bf16_f32 v76, v102, v103
	v_cvt_pk_bf16_f32 v77, v84, v85
	v_lshl_add_u64 v[78:79], v[132:133], 0, v[118:119]
	global_store_dwordx4 v[78:79], v[74:77], off
	s_waitcnt vmcnt(14)
	v_lshlrev_b32_e32 v78, 16, v86
	v_and_b32_e32 v79, 0xffff0000, v86
	v_pk_mul_f32 v[76:77], v[16:17], v[160:161]
	v_pk_mul_f32 v[84:85], v[4:5], v[162:163]
	v_pk_fma_f32 v[76:77], v[12:13], v[110:111], v[76:77]
	s_waitcnt vmcnt(13)
	v_lshlrev_b32_e32 v74, 16, v90
	v_and_b32_e32 v75, 0xffff0000, v90
	v_pk_fma_f32 v[76:77], v[20:21], v[78:79], v[76:77]
	v_lshlrev_b32_e32 v82, 16, v88
	v_and_b32_e32 v83, 0xffff0000, v88
	v_pk_fma_f32 v[84:85], v[0:1], v[112:113], v[84:85]
	v_pk_mul_f32 v[74:75], v[76:77], v[74:75]
	v_lshlrev_b32_e32 v76, 16, v92
	v_and_b32_e32 v77, 0xffff0000, v92
	v_pk_fma_f32 v[84:85], v[8:9], v[82:83], v[84:85]
	v_lshlrev_b32_e32 v86, 16, v91
	v_pk_mul_f32 v[76:77], v[84:85], v[76:77]
	v_lshlrev_b32_e32 v84, 16, v87
	v_and_b32_e32 v85, 0xffff0000, v87
	v_and_b32_e32 v87, 0xffff0000, v91
	v_pk_mul_f32 v[90:91], v[18:19], v[164:165]
	v_lshlrev_b32_e32 v88, 16, v89
	v_pk_fma_f32 v[90:91], v[14:15], v[114:115], v[90:91]
	v_and_b32_e32 v89, 0xffff0000, v89
	v_pk_fma_f32 v[90:91], v[22:23], v[84:85], v[90:91]
	v_cvt_pk_bf16_f32 v74, v74, v75
	v_pk_mul_f32 v[86:87], v[90:91], v[86:87]
	v_lshlrev_b32_e32 v90, 16, v93
	v_and_b32_e32 v91, 0xffff0000, v93
	v_pk_mul_f32 v[92:93], v[6:7], v[106:107]
	v_cvt_pk_bf16_f32 v75, v86, v87
	v_pk_fma_f32 v[92:93], v[2:3], v[116:117], v[92:93]
	v_cvt_pk_bf16_f32 v76, v76, v77
	v_pk_fma_f32 v[92:93], v[10:11], v[88:89], v[92:93]
	v_lshl_add_u64 v[86:87], v[132:133], 0, v[154:155]
	v_pk_mul_f32 v[90:91], v[92:93], v[90:91]
	v_pk_mul_f32 v[92:93], v[4:5], v[82:83]
	v_cvt_pk_bf16_f32 v77, v90, v91
	global_store_dwordx4 v[86:87], v[74:77], off
	s_waitcnt vmcnt(13)
	v_lshlrev_b32_e32 v86, 16, v94
	v_and_b32_e32 v87, 0xffff0000, v94
	v_pk_mul_f32 v[76:77], v[16:17], v[78:79]
	s_waitcnt vmcnt(12)
	v_lshlrev_b32_e32 v74, 16, v98
	v_pk_fma_f32 v[76:77], v[12:13], v[160:161], v[76:77]
	v_and_b32_e32 v75, 0xffff0000, v98
	v_pk_fma_f32 v[76:77], v[20:21], v[86:87], v[76:77]
	v_lshlrev_b32_e32 v90, 16, v96
	v_and_b32_e32 v91, 0xffff0000, v96
	v_pk_fma_f32 v[92:93], v[0:1], v[162:163], v[92:93]
	v_pk_mul_f32 v[74:75], v[76:77], v[74:75]
	v_lshlrev_b32_e32 v76, 16, v100
	v_and_b32_e32 v77, 0xffff0000, v100
	v_pk_fma_f32 v[92:93], v[8:9], v[90:91], v[92:93]
	v_lshlrev_b32_e32 v94, 16, v99
	v_pk_mul_f32 v[76:77], v[92:93], v[76:77]
	v_lshlrev_b32_e32 v92, 16, v95
	v_and_b32_e32 v93, 0xffff0000, v95
	v_and_b32_e32 v95, 0xffff0000, v99
	v_pk_mul_f32 v[98:99], v[18:19], v[84:85]
	v_lshlrev_b32_e32 v96, 16, v97
	v_pk_fma_f32 v[98:99], v[14:15], v[164:165], v[98:99]
	v_and_b32_e32 v97, 0xffff0000, v97
	v_pk_fma_f32 v[98:99], v[22:23], v[92:93], v[98:99]
	v_cvt_pk_bf16_f32 v74, v74, v75
	v_pk_mul_f32 v[94:95], v[98:99], v[94:95]
	v_lshlrev_b32_e32 v98, 16, v101
	v_and_b32_e32 v99, 0xffff0000, v101
	v_pk_mul_f32 v[100:101], v[6:7], v[88:89]
	v_cvt_pk_bf16_f32 v75, v94, v95
	v_pk_fma_f32 v[100:101], v[2:3], v[106:107], v[100:101]
	v_cvt_pk_bf16_f32 v76, v76, v77
	v_pk_fma_f32 v[100:101], v[10:11], v[96:97], v[100:101]
	v_lshl_add_u64 v[94:95], v[132:133], 0, v[156:157]
	v_pk_mul_f32 v[98:99], v[100:101], v[98:99]
	s_nop 0
	v_cvt_pk_bf16_f32 v77, v98, v99
	global_store_dwordx4 v[94:95], v[74:77], off
	v_pk_mul_f32 v[94:95], v[16:17], v[86:87]
	v_pk_mul_f32 v[98:99], v[4:5], v[90:91]
	s_waitcnt vmcnt(12)
	v_lshlrev_b32_e32 v74, 16, v60
	v_and_b32_e32 v75, 0xffff0000, v60
	v_pk_fma_f32 v[78:79], v[12:13], v[78:79], v[94:95]
	s_waitcnt vmcnt(11)
	v_lshlrev_b32_e32 v76, 16, v56
	v_and_b32_e32 v77, 0xffff0000, v56
	v_pk_fma_f32 v[78:79], v[20:21], v[74:75], v[78:79]
	v_pk_fma_f32 v[82:83], v[0:1], v[82:83], v[98:99]
	v_pk_mul_f32 v[76:77], v[78:79], v[76:77]
	v_lshlrev_b32_e32 v78, 16, v62
	v_and_b32_e32 v79, 0xffff0000, v62
	v_lshlrev_b32_e32 v94, 16, v58
	v_and_b32_e32 v95, 0xffff0000, v58
	v_pk_fma_f32 v[82:83], v[8:9], v[78:79], v[82:83]
	v_lshlrev_b32_e32 v60, 16, v61
	v_pk_mul_f32 v[82:83], v[82:83], v[94:95]
	v_pk_mul_f32 v[94:95], v[18:19], v[92:93]
	v_and_b32_e32 v61, 0xffff0000, v61
	v_pk_fma_f32 v[84:85], v[14:15], v[84:85], v[94:95]
	v_lshlrev_b32_e32 v56, 16, v57
	v_and_b32_e32 v57, 0xffff0000, v57
	v_pk_fma_f32 v[84:85], v[22:23], v[60:61], v[84:85]
	v_lshlrev_b32_e32 v62, 16, v63
	v_pk_mul_f32 v[84:85], v[84:85], v[56:57]
	v_lshlrev_b32_e32 v56, 16, v59
	v_and_b32_e32 v57, 0xffff0000, v59
	v_pk_mul_f32 v[58:59], v[6:7], v[96:97]
	v_and_b32_e32 v63, 0xffff0000, v63
	v_pk_fma_f32 v[58:59], v[2:3], v[88:89], v[58:59]
	s_nop 0
	v_pk_fma_f32 v[58:59], v[10:11], v[62:63], v[58:59]
	s_nop 0
	v_pk_mul_f32 v[88:89], v[58:59], v[56:57]
	v_cvt_pk_bf16_f32 v56, v76, v77
	v_cvt_pk_bf16_f32 v57, v84, v85
	v_cvt_pk_bf16_f32 v58, v82, v83
	v_cvt_pk_bf16_f32 v59, v88, v89
	global_store_dwordx4 v[72:73], v[56:59], off
	v_pk_mul_f32 v[72:73], v[16:17], v[74:75]
	v_pk_mul_f32 v[82:83], v[4:5], v[78:79]
	s_waitcnt vmcnt(11)
	v_lshlrev_b32_e32 v56, 16, v52
	v_and_b32_e32 v57, 0xffff0000, v52
	v_pk_fma_f32 v[72:73], v[12:13], v[86:87], v[72:73]
	s_waitcnt vmcnt(10)
	v_lshlrev_b32_e32 v58, 16, v48
	v_and_b32_e32 v59, 0xffff0000, v48
	v_pk_fma_f32 v[72:73], v[20:21], v[56:57], v[72:73]
	v_pk_fma_f32 v[82:83], v[0:1], v[90:91], v[82:83]
	v_pk_mul_f32 v[58:59], v[72:73], v[58:59]
	v_lshlrev_b32_e32 v72, 16, v54
	v_and_b32_e32 v73, 0xffff0000, v54
	v_lshlrev_b32_e32 v76, 16, v50
	v_and_b32_e32 v77, 0xffff0000, v50
	v_pk_fma_f32 v[82:83], v[8:9], v[72:73], v[82:83]
	v_lshlrev_b32_e32 v52, 16, v53
	v_pk_mul_f32 v[76:77], v[82:83], v[76:77]
	v_pk_mul_f32 v[82:83], v[18:19], v[60:61]
	v_and_b32_e32 v53, 0xffff0000, v53
	v_pk_fma_f32 v[82:83], v[14:15], v[92:93], v[82:83]
	v_lshlrev_b32_e32 v48, 16, v49
	v_and_b32_e32 v49, 0xffff0000, v49
	v_pk_fma_f32 v[82:83], v[22:23], v[52:53], v[82:83]
	v_lshlrev_b32_e32 v54, 16, v55
	v_pk_mul_f32 v[82:83], v[82:83], v[48:49]
	v_lshlrev_b32_e32 v48, 16, v51
	v_and_b32_e32 v49, 0xffff0000, v51
	v_pk_mul_f32 v[50:51], v[6:7], v[62:63]
	v_and_b32_e32 v55, 0xffff0000, v55
	v_pk_fma_f32 v[50:51], v[2:3], v[96:97], v[50:51]
	s_nop 0
	v_pk_fma_f32 v[50:51], v[10:11], v[54:55], v[50:51]
	s_nop 0
	v_pk_mul_f32 v[84:85], v[50:51], v[48:49]
	v_cvt_pk_bf16_f32 v48, v58, v59
	v_cvt_pk_bf16_f32 v49, v82, v83
	v_cvt_pk_bf16_f32 v50, v76, v77
	v_cvt_pk_bf16_f32 v51, v84, v85
	v_lshl_add_u64 v[58:59], v[132:133], 0, v[70:71]
	global_store_dwordx4 v[58:59], v[48:51], off
	v_pk_mul_f32 v[58:59], v[16:17], v[56:57]
	s_waitcnt vmcnt(9)
	v_lshlrev_b32_e32 v70, 16, v42
	v_lshlrev_b32_e32 v48, 16, v44
	v_and_b32_e32 v49, 0xffff0000, v44
	v_pk_fma_f32 v[58:59], v[12:13], v[74:75], v[58:59]
	v_lshlrev_b32_e32 v50, 16, v40
	v_and_b32_e32 v51, 0xffff0000, v40
	v_pk_fma_f32 v[58:59], v[20:21], v[48:49], v[58:59]
	v_pk_mul_f32 v[74:75], v[4:5], v[72:73]
	v_pk_mul_f32 v[50:51], v[58:59], v[50:51]
	v_lshlrev_b32_e32 v58, 16, v46
	v_and_b32_e32 v59, 0xffff0000, v46
	v_pk_fma_f32 v[74:75], v[0:1], v[78:79], v[74:75]
	v_and_b32_e32 v71, 0xffff0000, v42
	v_pk_fma_f32 v[74:75], v[8:9], v[58:59], v[74:75]
	v_lshlrev_b32_e32 v40, 16, v41
	v_pk_mul_f32 v[70:71], v[74:75], v[70:71]
	v_lshlrev_b32_e32 v74, 16, v45
	v_and_b32_e32 v75, 0xffff0000, v45
	v_pk_mul_f32 v[44:45], v[18:19], v[52:53]
	v_and_b32_e32 v41, 0xffff0000, v41
	v_pk_fma_f32 v[44:45], v[14:15], v[60:61], v[44:45]
	v_lshlrev_b32_e32 v60, 16, v47
	v_pk_fma_f32 v[44:45], v[22:23], v[74:75], v[44:45]
	v_and_b32_e32 v61, 0xffff0000, v47
	v_pk_mul_f32 v[44:45], v[44:45], v[40:41]
	v_lshlrev_b32_e32 v40, 16, v43
	v_and_b32_e32 v41, 0xffff0000, v43
	v_pk_mul_f32 v[42:43], v[6:7], v[54:55]
	s_nop 0
	v_pk_fma_f32 v[42:43], v[2:3], v[62:63], v[42:43]
	s_nop 0
	v_pk_fma_f32 v[42:43], v[10:11], v[60:61], v[42:43]
	s_nop 0
	v_pk_mul_f32 v[46:47], v[42:43], v[40:41]
	v_cvt_pk_bf16_f32 v40, v50, v51
	v_cvt_pk_bf16_f32 v41, v44, v45
	v_cvt_pk_bf16_f32 v42, v70, v71
	v_cvt_pk_bf16_f32 v43, v46, v47
	v_lshl_add_u64 v[44:45], v[132:133], 0, v[68:69]
	global_store_dwordx4 v[44:45], v[40:43], off
	v_pk_mul_f32 v[44:45], v[16:17], v[48:49]
	v_pk_mul_f32 v[46:47], v[4:5], v[58:59]
	s_waitcnt vmcnt(9)
	v_lshlrev_b32_e32 v40, 16, v36
	v_and_b32_e32 v41, 0xffff0000, v36
	v_pk_fma_f32 v[44:45], v[12:13], v[56:57], v[44:45]
	s_waitcnt vmcnt(8)
	v_lshlrev_b32_e32 v42, 16, v32
	v_and_b32_e32 v43, 0xffff0000, v32
	v_pk_fma_f32 v[44:45], v[20:21], v[40:41], v[44:45]
	v_pk_fma_f32 v[46:47], v[0:1], v[72:73], v[46:47]
	v_pk_mul_f32 v[50:51], v[44:45], v[42:43]
	v_lshlrev_b32_e32 v44, 16, v38
	v_and_b32_e32 v45, 0xffff0000, v38
	v_lshlrev_b32_e32 v42, 16, v34
	v_and_b32_e32 v43, 0xffff0000, v34
	v_pk_fma_f32 v[46:47], v[8:9], v[44:45], v[46:47]
	v_lshlrev_b32_e32 v32, 16, v33
	v_pk_mul_f32 v[56:57], v[46:47], v[42:43]
	v_lshlrev_b32_e32 v42, 16, v37
	v_and_b32_e32 v43, 0xffff0000, v37
	v_pk_mul_f32 v[36:37], v[18:19], v[74:75]
	v_and_b32_e32 v33, 0xffff0000, v33
	v_pk_fma_f32 v[36:37], v[14:15], v[52:53], v[36:37]
	v_lshlrev_b32_e32 v46, 16, v39
	v_pk_fma_f32 v[36:37], v[22:23], v[42:43], v[36:37]
	v_and_b32_e32 v47, 0xffff0000, v39
	v_pk_mul_f32 v[36:37], v[36:37], v[32:33]
	v_lshlrev_b32_e32 v32, 16, v35
	v_and_b32_e32 v33, 0xffff0000, v35
	v_pk_mul_f32 v[34:35], v[6:7], v[60:61]
	v_pk_mul_f32 v[16:17], v[16:17], v[40:41]
	v_pk_fma_f32 v[34:35], v[2:3], v[54:55], v[34:35]
	v_pk_fma_f32 v[12:13], v[12:13], v[48:49], v[16:17]
	v_pk_fma_f32 v[34:35], v[10:11], v[46:47], v[34:35]
	v_pk_mul_f32 v[4:5], v[4:5], v[44:45]
	v_pk_mul_f32 v[38:39], v[34:35], v[32:33]
	v_cvt_pk_bf16_f32 v32, v50, v51
	v_cvt_pk_bf16_f32 v33, v36, v37
	v_cvt_pk_bf16_f32 v34, v56, v57
	v_cvt_pk_bf16_f32 v35, v38, v39
	v_lshl_add_u64 v[36:37], v[132:133], 0, v[66:67]
	global_store_dwordx4 v[36:37], v[32:35], off
	v_pk_fma_f32 v[0:1], v[0:1], v[58:59], v[4:5]
	v_pk_mul_f32 v[6:7], v[6:7], v[46:47]
	s_waitcnt vmcnt(8)
	v_lshlrev_b32_e32 v32, 16, v28
	v_and_b32_e32 v33, 0xffff0000, v28
	s_waitcnt vmcnt(7)
	v_lshlrev_b32_e32 v34, 16, v24
	v_and_b32_e32 v35, 0xffff0000, v24
	v_pk_fma_f32 v[12:13], v[20:21], v[32:33], v[12:13]
	v_lshlrev_b32_e32 v20, 16, v26
	v_pk_mul_f32 v[16:17], v[12:13], v[34:35]
	v_lshlrev_b32_e32 v12, 16, v30
	v_and_b32_e32 v13, 0xffff0000, v30
	v_pk_fma_f32 v[0:1], v[8:9], v[12:13], v[0:1]
	v_pk_mul_f32 v[8:9], v[18:19], v[42:43]
	v_and_b32_e32 v21, 0xffff0000, v26
	v_lshlrev_b32_e32 v34, 16, v29
	v_and_b32_e32 v35, 0xffff0000, v29
	v_pk_fma_f32 v[8:9], v[14:15], v[74:75], v[8:9]
	v_pk_mul_f32 v[4:5], v[0:1], v[20:21]
	v_lshlrev_b32_e32 v0, 16, v25
	v_and_b32_e32 v1, 0xffff0000, v25
	v_pk_fma_f32 v[8:9], v[22:23], v[34:35], v[8:9]
	v_lshlrev_b32_e32 v14, 16, v31
	v_and_b32_e32 v15, 0xffff0000, v31
	v_pk_fma_f32 v[2:3], v[2:3], v[60:61], v[6:7]
	v_pk_mul_f32 v[8:9], v[8:9], v[0:1]
	v_lshlrev_b32_e32 v0, 16, v27
	v_and_b32_e32 v1, 0xffff0000, v27
	v_pk_fma_f32 v[2:3], v[10:11], v[14:15], v[2:3]
	s_nop 0
	v_pk_mul_f32 v[6:7], v[2:3], v[0:1]
	v_cvt_pk_bf16_f32 v0, v16, v17
	v_cvt_pk_bf16_f32 v1, v8, v9
	v_cvt_pk_bf16_f32 v2, v4, v5
	v_cvt_pk_bf16_f32 v3, v6, v7
	v_lshl_add_u64 v[4:5], v[132:133], 0, v[64:65]
	global_store_dwordx4 v[4:5], v[0:3], off
	s_nop 1
	v_or_b32_e32 v0, 15, v104
	v_cndmask_b32_e32 v1, 31, v243, vcc
	v_cmp_eq_u32_e64 s[0:1], v0, v1
	s_and_saveexec_b64 s[10:11], s[0:1]
	s_cbranch_execz .LBB0_410
	v_ashrrev_i32_e32 v0, 11, v80
	v_mov_b32_e32 v1, s31
	v_mov_b32_e32 v2, s49
	v_cndmask_b32_e32 v0, v194, v0, vcc
	v_cndmask_b32_e32 v3, v1, v2, vcc
	v_mov_b32_e32 v1, s30
	v_mov_b32_e32 v2, s48
	v_cndmask_b32_e32 v2, v1, v2, vcc
	v_ashrrev_i32_e32 v1, 31, v0
	v_lshlrev_b64 v[0:1], 13, v[0:1]
	v_lshl_add_u64 v[0:1], v[2:3], 0, v[0:1]
	v_lshlrev_b32_e32 v194, 2, v120
	v_lshl_add_u64 v[0:1], v[0:1], 0, v[194:195]
	global_store_dwordx4 v[0:1], v[40:43], off
	global_store_dwordx4 v[0:1], v[44:47], off offset:16
	v_add_co_u32_e32 v0, vcc, 0x1000, v0
	s_nop 1
	v_addc_co_u32_e32 v1, vcc, 0, v1, vcc
	global_store_dwordx4 v[0:1], v[32:35], off
	global_store_dwordx4 v[0:1], v[12:15], off offset:16
	s_branch .LBB0_410

.LBB0_439:
	s_or_b64 exec, exec, s[0:1]
	v_lshrrev_b32_e32 v0, 1, v65
	v_and_b32_e32 v3, 32, v0
	v_and_b32_e32 v66, 31, v65
	v_or_b32_e32 v67, v3, v66
	v_ashrrev_i32_e32 v2, 7, v65
	v_add_u32_e32 v4, v67, v1
	v_lshl_add_u32 v2, s20, 2, v2
	v_ashrrev_i32_e32 v5, 31, v4
	v_lshlrev_b64 v[4:5], 11, v[4:5]
	v_lshlrev_b32_e32 v6, 6, v2
	v_lshl_add_u64 v[4:5], s[44:45], 0, v[4:5]
	v_ashrrev_i32_e32 v7, 31, v6
	v_cmp_gt_i32_e64 s[0:1], s16, v3
	v_lshl_add_u64 v[154:155], v[6:7], 1, v[4:5]
	s_and_saveexec_b64 s[10:11], s[0:1]
	s_cbranch_execz .LBB0_441
	s_cmp_lg_u32 s101, 0
	s_cbranch_scc1 .Lswa_qhave
	v_and_b32_e32 v194, 16, v0
	v_lshl_add_u64 v[0:1], v[154:155], 0, v[194:195]
	global_load_dwordx4 v[136:139], v[0:1], off nt
	global_load_dwordx4 v[140:143], v[0:1], off offset:32 nt
	global_load_dwordx4 v[144:147], v[0:1], off offset:64 nt
	global_load_dwordx4 v[148:151], v[0:1], off offset:96 nt
	s_waitcnt vmcnt(0)

.LBB0_446:
	v_lshlrev_b32_e32 v0, 3, v4
	s_lshl_b32 s33, s89, 3
	s_and_b32 s54, s88, 3
	v_lshrrev_b32_e32 v134, 1, v121
	v_and_b32_e32 v135, 32, v134
	v_cmp_gt_i32_e64 s[28:29], s51, v135
	v_and_b32_e32 v152, 31, v121
	v_or_b32_e32 v152, v135, v152
	v_add_u32_e32 v152, s50, v152
	v_ashrrev_i32_e32 v153, 31, v152
	v_lshlrev_b64 v[152:153], 11, v[152:153]
	v_lshl_add_u64 v[152:153], s[44:45], 0, v[152:153]
	v_ashrrev_i32_e32 v135, 7, v121
	v_lshl_add_u32 v135, s54, 2, v135
	v_lshlrev_b32_e32 v135, 7, v135
	v_and_b32_e32 v134, 16, v134
	v_add_u32_e32 v134, v135, v134
	v_mov_b32_e32 v135, 0
	v_lshl_add_u64 v[152:153], v[152:153], 0, v[134:135]
	s_and_saveexec_b64 s[28:29], s[28:29]
	global_load_dwordx4 v[136:139], v[152:153], off nt
	global_load_dwordx4 v[140:143], v[152:153], off offset:32 nt
	global_load_dwordx4 v[144:147], v[152:153], off offset:64 nt
	global_load_dwordx4 v[148:151], v[152:153], off offset:96 nt
	s_or_b64 exec, exec, s[28:29]
	s_mov_b32 s101, 1
	v_and_b32_e32 v3, 56, v0
	v_cmp_gt_i32_e32 vcc, s33, v4
	s_and_saveexec_b64 s[24:25], vcc
	s_cbranch_execz .LBB0_452
	v_ashrrev_i32_e32 v0, 3, v4
	v_cmp_lt_i32_e32 vcc, s83, v0
	s_xor_b64 s[28:29], s[22:23], -1
	s_or_b64 s[28:29], s[28:29], vcc
	s_lshl_b32 s92, s54, 6
	s_and_saveexec_b64 s[42:43], s[28:29]
	s_xor_b64 s[28:29], exec, s[42:43]
	s_cbranch_execz .LBB0_449
	v_add_u32_e32 v0, s26, v0
	v_ashrrev_i32_e32 v1, 31, v0
	v_readlane_b32 s42, v254, 23
	v_lshlrev_b64 v[0:1], 10, v[0:1]
	v_readlane_b32 s43, v254, 24
	v_lshlrev_b32_e32 v194, 1, v3
	s_nop 0
	v_lshl_add_u64 v[0:1], s[42:43], 0, v[0:1]
	s_lshl_b32 s42, s92, 1
	s_mov_b32 s43, s93
	v_lshl_add_u64 v[0:1], v[0:1], 0, s[42:43]
	v_lshl_add_u64 v[0:1], v[0:1], 0, v[194:195]
	global_load_dwordx4 v[80:83], v[0:1], off
	global_load_dwordx4 v[92:95], v[0:1], off offset:512
